# v007 + P14 final LayerNorm: gain/bias vectors of 8 blocks loaded up front
# baseline (speedup 1.0000x reference)
; #define GAS __attribute__((address_space(1)))
; __device__ __forceinline__ void ln_stats(const v4f (&v)[16], float& mean, float& rstd) {
;     float s = 0.f;
; #pragma unroll
;     for (int j = 0; j < 16; ++j) s += (v[j].x + v[j].y) + (v[j].z + v[j].w);
;     mean = wave_sum(s) * (1.f / D_MODEL); float s2 = 0.f;
; __device__ __forceinline__ void phase_ln_final(const Ctx& X, float* io, const float* g, const float* bt) {
;     for (int m = X.gw; m < MTOK; m += X.NGW) {
;         GAS v4f* rr = (GAS v4f*)(io + (size_t)m * D_MODEL) + X.lane;
;         v4f v[16];
; #pragma unroll
;         for (int j = 0; j < 16; ++j) v[j] = rr[64 * j];
;         float mean, rstd; ln_stats(v, mean, rstd);
;         const GAS v4f* gp = (const GAS v4f*)g + X.lane; const GAS v4f* bp = (const GAS v4f*)bt + X.lane;
; #pragma unroll
;         for (int j = 0; j < 16; ++j) rr[64 * j] = (v[j] - mean) * rstd * gp[64 * j] + bp[64 * j];
.LBB0_1392:
	global_load_dwordx4 v[12:15], v[124:125], off
	global_load_dwordx4 v[8:11], v[124:125], off offset:1024
	global_load_dwordx4 v[4:7], v[124:125], off offset:2048
	global_load_dwordx4 v[0:3], v[124:125], off offset:3072
	v_add_co_u32_e32 v126, vcc, 0x1000, v124
	global_load_dwordx4 v[64:67], v[72:73], off
	global_load_dwordx4 v[68:71], v[74:75], off
	v_addc_co_u32_e32 v127, vcc, 0, v125, vcc
	global_load_dwordx4 v[60:63], v[126:127], off
	global_load_dwordx4 v[56:59], v[126:127], off offset:1024
	global_load_dwordx4 v[52:55], v[126:127], off offset:2048
	global_load_dwordx4 v[48:51], v[126:127], off offset:3072
	v_add_co_u32_e32 v130, vcc, 0x2000, v124
	s_add_i32 s2, s2, s4
	s_nop 0
	v_addc_co_u32_e32 v131, vcc, 0, v125, vcc
	global_load_dwordx4 v[44:47], v[130:131], off
	global_load_dwordx4 v[40:43], v[130:131], off offset:1024
	global_load_dwordx4 v[36:39], v[130:131], off offset:2048
	global_load_dwordx4 v[32:35], v[130:131], off offset:3072
	v_add_co_u32_e32 v128, vcc, 0x3000, v124
	s_cmpk_lt_i32 s2, 0x4000
	s_nop 0
	v_addc_co_u32_e32 v129, vcc, 0, v125, vcc
	global_load_dwordx4 v[28:31], v[128:129], off
	global_load_dwordx4 v[24:27], v[128:129], off offset:1024
	global_load_dwordx4 v[20:23], v[128:129], off offset:2048
	global_load_dwordx4 v[16:19], v[128:129], off offset:3072
	global_load_dwordx4 v[186:189], v[72:73], off offset:1024
	global_load_dwordx4 v[190:193], v[74:75], off offset:1024
	global_load_dwordx4 v[194:197], v[72:73], off offset:2048
	global_load_dwordx4 v[198:201], v[74:75], off offset:2048
	global_load_dwordx4 v[202:205], v[72:73], off offset:3072
	global_load_dwordx4 v[206:209], v[74:75], off offset:3072
	global_load_dwordx4 v[210:213], v[76:77], off
	global_load_dwordx4 v[214:217], v[78:79], off
	global_load_dwordx4 v[218:221], v[80:81], off
	global_load_dwordx4 v[222:225], v[82:83], off
	global_load_dwordx4 v[226:229], v[84:85], off
	global_load_dwordx4 v[230:233], v[86:87], off
	global_load_dwordx4 v[234:237], v[88:89], off
	global_load_dwordx4 v[238:241], v[90:91], off
	global_load_dwordx4 v[242:245], v[92:93], off
	global_load_dwordx4 v[246:249], v[94:95], off
	s_waitcnt vmcnt(33)
	v_mov_b32_e32 v140, v13
	v_mov_b32_e32 v141, v14
	v_mov_b32_e32 v142, v12
	v_mov_b32_e32 v143, v15
	s_waitcnt vmcnt(32)
	v_mov_b32_e32 v144, v9
	v_mov_b32_e32 v145, v10
	v_mov_b32_e32 v146, v8
	v_mov_b32_e32 v147, v11
	v_pk_add_f32 v[140:141], v[140:141], v[142:143]
	v_pk_add_f32 v[142:143], v[144:145], v[146:147]
	v_add_f32_e32 v152, v140, v141
	v_pk_add_f32 v[140:141], v[142:143], v[142:143] op_sel:[0,1] op_sel_hi:[1,0]
	s_waitcnt vmcnt(31)
	v_add_f32_e32 v148, v4, v5
	v_add_f32_e32 v150, v6, v7
	s_waitcnt vmcnt(30)
	v_mov_b32_e32 v153, v0
	v_mov_b32_e32 v149, v2
	v_mov_b32_e32 v151, v3
	v_add_f32_e32 v152, 0, v152
	v_mov_b32_e32 v141, v1
	v_pk_add_f32 v[144:145], v[148:149], v[150:151]
	s_waitcnt vmcnt(27)
	v_mov_b32_e32 v142, v61
	v_mov_b32_e32 v143, v62
	v_mov_b32_e32 v146, v60
	v_mov_b32_e32 v147, v63
	v_pk_add_f32 v[140:141], v[152:153], v[140:141]
	v_pk_add_f32 v[142:143], v[142:143], v[146:147]
	v_pk_add_f32 v[140:141], v[140:141], v[144:145]
	v_pk_add_f32 v[142:143], v[142:143], v[142:143] op_sel:[0,1] op_sel_hi:[1,0]
	v_pk_add_f32 v[140:141], v[140:141], v[140:141] op_sel:[0,1] op_sel_hi:[1,0]
	s_waitcnt vmcnt(26)
	v_add_f32_e32 v148, v56, v57
	v_add_f32_e32 v150, v58, v59
	s_waitcnt vmcnt(25)
	v_mov_b32_e32 v149, v54
	v_mov_b32_e32 v151, v55
	v_mov_b32_e32 v143, v53
	v_mov_b32_e32 v141, v52
	s_waitcnt vmcnt(24)
	v_mov_b32_e32 v154, v49
	v_mov_b32_e32 v155, v50
	v_mov_b32_e32 v156, v48
	v_mov_b32_e32 v157, v51
	v_pk_add_f32 v[146:147], v[148:149], v[150:151]
	v_pk_add_f32 v[140:141], v[140:141], v[142:143]
	v_pk_add_f32 v[148:149], v[154:155], v[156:157]
	v_pk_add_f32 v[140:141], v[140:141], v[146:147]
	v_pk_add_f32 v[148:149], v[148:149], v[148:149] op_sel:[0,1] op_sel_hi:[1,0]
	v_pk_add_f32 v[140:141], v[140:141], v[140:141] op_sel:[0,1] op_sel_hi:[1,0]
	s_waitcnt vmcnt(23)
	v_add_f32_e32 v150, v44, v45
	v_add_f32_e32 v154, v46, v47
	s_waitcnt vmcnt(22)
	v_mov_b32_e32 v151, v42
	v_mov_b32_e32 v155, v43
	v_mov_b32_e32 v149, v41
	v_mov_b32_e32 v141, v40
	s_waitcnt vmcnt(21)
	v_mov_b32_e32 v156, v37
	v_mov_b32_e32 v157, v38
	v_mov_b32_e32 v158, v36
	v_mov_b32_e32 v159, v39
	v_pk_add_f32 v[150:151], v[150:151], v[154:155]
	v_pk_add_f32 v[140:141], v[140:141], v[148:149]
	v_pk_add_f32 v[152:153], v[156:157], v[158:159]
	v_pk_add_f32 v[140:141], v[140:141], v[150:151]
	v_pk_add_f32 v[144:145], v[152:153], v[152:153] op_sel:[0,1] op_sel_hi:[1,0]
	v_pk_add_f32 v[140:141], v[140:141], v[140:141] op_sel:[0,1] op_sel_hi:[1,0]
	s_waitcnt vmcnt(20)
	v_add_f32_e32 v160, v32, v33
	v_add_f32_e32 v162, v34, v35
	s_waitcnt vmcnt(19)
	v_mov_b32_e32 v161, v30
	v_mov_b32_e32 v163, v31
	v_mov_b32_e32 v145, v29
	v_mov_b32_e32 v141, v28
	s_waitcnt vmcnt(18)
	v_mov_b32_e32 v154, v25
	v_mov_b32_e32 v155, v26
	v_mov_b32_e32 v156, v24
	v_mov_b32_e32 v157, v27
	v_pk_add_f32 v[152:153], v[160:161], v[162:163]
	v_pk_add_f32 v[140:141], v[140:141], v[144:145]
	v_pk_add_f32 v[154:155], v[154:155], v[156:157]
	v_pk_add_f32 v[140:141], v[140:141], v[152:153]
	v_pk_add_f32 v[154:155], v[154:155], v[154:155] op_sel:[0,1] op_sel_hi:[1,0]
	v_pk_add_f32 v[140:141], v[140:141], v[140:141] op_sel:[0,1] op_sel_hi:[1,0]
	s_waitcnt vmcnt(17)
	v_add_f32_e32 v158, v20, v21
	v_add_f32_e32 v164, v22, v23
	s_waitcnt vmcnt(16)
	v_mov_b32_e32 v159, v18
	v_mov_b32_e32 v165, v19
	v_mov_b32_e32 v155, v17
	v_mov_b32_e32 v141, v16
	v_pk_add_f32 v[156:157], v[158:159], v[164:165]
	v_pk_add_f32 v[140:141], v[140:141], v[154:155]
	s_nop 0
	v_pk_add_f32 v[140:141], v[140:141], v[156:157]
	s_nop 0
	v_add_f32_e32 v140, v140, v141
	ds_bpermute_b32 v141, v132, v140
	s_waitcnt lgkmcnt(0)
; __device__ __forceinline__ void ln_stats(const v4f (&v)[16], float& mean, float& rstd) {
;     float s = 0.f;
; #pragma unroll
;     for (int j = 0; j < 16; ++j) s += (v[j].x + v[j].y) + (v[j].z + v[j].w);
;     mean = wave_sum(s) * (1.f / D_MODEL); float s2 = 0.f;
; #pragma unroll
;     for (int j = 0; j < 16; ++j) { const v4f d = v[j] - mean; s2 += (d.x * d.x + d.y * d.y) + (d.z * d.z + d.w * d.w); }
;     rstd = 1.0f / sqrtf(wave_sum(s2) * (1.f / D_MODEL) + LN_EPS);
	v_add_f32_e32 v140, v140, v141
	ds_bpermute_b32 v141, v133, v140
	s_waitcnt lgkmcnt(0)
	v_add_f32_e32 v140, v140, v141
	ds_bpermute_b32 v141, v134, v140
	s_waitcnt lgkmcnt(0)
	v_add_f32_e32 v140, v140, v141
	ds_bpermute_b32 v141, v135, v140
	s_waitcnt lgkmcnt(0)
	v_add_f32_e32 v140, v140, v141
	ds_bpermute_b32 v141, v136, v140
	s_waitcnt lgkmcnt(0)
	v_add_f32_e32 v140, v140, v141
	ds_bpermute_b32 v141, v137, v140
	s_waitcnt lgkmcnt(0)
	v_add_f32_e32 v148, v140, v141
	v_fmamk_f32 v141, v148, 0xb9800000, v13
	v_fmamk_f32 v140, v148, 0xb9800000, v12
	v_fmamk_f32 v15, v148, 0xb9800000, v15
	v_fmac_f32_e32 v14, 0xb9800000, v148
	v_fmamk_f32 v143, v148, 0xb9800000, v9
	v_fmamk_f32 v142, v148, 0xb9800000, v8
	v_fmamk_f32 v11, v148, 0xb9800000, v11
	v_fmac_f32_e32 v10, 0xb9800000, v148
	v_fmamk_f32 v145, v148, 0xb9800000, v5
	v_fmamk_f32 v144, v148, 0xb9800000, v4
	v_fmamk_f32 v147, v148, 0xb9800000, v3
	v_fmamk_f32 v146, v148, 0xb9800000, v2
	v_fmamk_f32 v13, v148, 0xb9800000, v31
	v_fmamk_f32 v12, v148, 0xb9800000, v30
	v_fmamk_f32 v9, v148, 0xb9800000, v25
	v_fmamk_f32 v8, v148, 0xb9800000, v24
	v_fmamk_f32 v5, v148, 0xb9800000, v21
	v_fmamk_f32 v4, v148, 0xb9800000, v20
	v_fmamk_f32 v3, v148, 0xb9800000, v19
	v_fmamk_f32 v2, v148, 0xb9800000, v18
	v_pk_mul_f32 v[18:19], v[14:15], v[14:15]
	v_pk_mul_f32 v[20:21], v[140:141], v[140:141]
	v_pk_mul_f32 v[24:25], v[10:11], v[10:11]
	v_pk_mul_f32 v[30:31], v[142:143], v[142:143]
	v_fmac_f32_e32 v6, 0xb9800000, v148
	v_pk_mov_b32 v[184:185], v[20:21], v[18:19] op_sel:[1,0]
	v_mov_b32_e32 v21, v19
	v_pk_mov_b32 v[18:19], v[30:31], v[24:25] op_sel:[1,0]
	v_mov_b32_e32 v31, v25
	v_fmamk_f32 v7, v148, 0xb9800000, v7
	v_fmamk_f32 v1, v148, 0xb9800000, v1
	v_fmac_f32_e32 v0, 0xb9800000, v148
	v_fmamk_f32 v61, v148, 0xb9800000, v61
	v_fmamk_f32 v60, v148, 0xb9800000, v60
	v_fmamk_f32 v63, v148, 0xb9800000, v63
	v_fmac_f32_e32 v62, 0xb9800000, v148
	v_fmamk_f32 v57, v148, 0xb9800000, v57
	v_fmamk_f32 v56, v148, 0xb9800000, v56
	v_fmamk_f32 v59, v148, 0xb9800000, v59
	v_fmac_f32_e32 v58, 0xb9800000, v148
	v_fmamk_f32 v55, v148, 0xb9800000, v55
	v_fmamk_f32 v54, v148, 0xb9800000, v54
	v_fmamk_f32 v53, v148, 0xb9800000, v53
	v_fmac_f32_e32 v52, 0xb9800000, v148
	v_fmamk_f32 v49, v148, 0xb9800000, v49
	v_fmamk_f32 v48, v148, 0xb9800000, v48
	v_fmamk_f32 v51, v148, 0xb9800000, v51
	v_fmac_f32_e32 v50, 0xb9800000, v148
	v_fmamk_f32 v45, v148, 0xb9800000, v45
	v_fmamk_f32 v44, v148, 0xb9800000, v44
	v_fmamk_f32 v47, v148, 0xb9800000, v47
	v_fmac_f32_e32 v46, 0xb9800000, v148
	v_fmamk_f32 v43, v148, 0xb9800000, v43
	v_fmamk_f32 v42, v148, 0xb9800000, v42
	v_fmamk_f32 v41, v148, 0xb9800000, v41
	v_fmac_f32_e32 v40, 0xb9800000, v148
	v_fmamk_f32 v37, v148, 0xb9800000, v37
	v_fmamk_f32 v36, v148, 0xb9800000, v36
	v_fmamk_f32 v39, v148, 0xb9800000, v39
	v_fmac_f32_e32 v38, 0xb9800000, v148
	v_fmamk_f32 v33, v148, 0xb9800000, v33
	v_fmamk_f32 v32, v148, 0xb9800000, v32
	v_fmamk_f32 v35, v148, 0xb9800000, v35
	v_fmac_f32_e32 v34, 0xb9800000, v148
	v_fmamk_f32 v29, v148, 0xb9800000, v29
	v_fmac_f32_e32 v28, 0xb9800000, v148
	v_fmamk_f32 v27, v148, 0xb9800000, v27
	v_fmac_f32_e32 v26, 0xb9800000, v148
	v_fmamk_f32 v23, v148, 0xb9800000, v23
	v_fmac_f32_e32 v22, 0xb9800000, v148
	v_fmamk_f32 v17, v148, 0xb9800000, v17
	v_fmac_f32_e32 v16, 0xb9800000, v148
	v_mul_f32_e32 v148, v144, v144
	v_mul_f32_e32 v150, v6, v6
	v_pk_add_f32 v[20:21], v[184:185], v[20:21]
	v_pk_add_f32 v[18:19], v[18:19], v[30:31]
	v_pk_fma_f32 v[24:25], v[144:145], v[144:145], v[148:149] op_sel_hi:[1,1,0]
	v_pk_fma_f32 v[148:149], v[6:7], v[6:7], v[150:151] op_sel_hi:[1,1,0]
	v_pk_add_f32 v[20:21], v[20:21], v[20:21] op_sel_hi:[0,1]
	v_pk_add_f32 v[18:19], v[18:19], v[18:19] op_sel_hi:[0,1]
	v_pk_mul_f32 v[152:153], v[62:63], v[62:63]
	v_pk_mul_f32 v[154:155], v[60:61], v[60:61]
	v_mul_f32_e32 v24, v0, v0
	v_mul_f32_e32 v148, v1, v1
	v_mul_f32_e32 v20, v146, v146
	v_mul_f32_e32 v18, v147, v147
	v_pk_mov_b32 v[150:151], v[154:155], v[152:153] op_sel:[1,0]
	v_mov_b32_e32 v155, v153
	v_pk_add_f32 v[24:25], v[24:25], v[148:149]
	v_pk_add_f32 v[18:19], v[20:21], v[18:19]
	v_mul_f32_e32 v156, v56, v56
	v_mul_f32_e32 v158, v58, v58
	v_pk_add_f32 v[30:31], v[150:151], v[154:155]
	v_pk_add_f32 v[18:19], v[24:25], v[18:19]
	v_pk_fma_f32 v[152:153], v[56:57], v[56:57], v[156:157] op_sel_hi:[1,1,0]
	v_pk_fma_f32 v[156:157], v[58:59], v[58:59], v[158:159] op_sel_hi:[1,1,0]
	v_pk_add_f32 v[30:31], v[30:31], v[30:31] op_sel_hi:[0,1]
	v_pk_add_f32 v[18:19], v[18:19], v[18:19] op_sel_hi:[0,1]
	v_pk_mul_f32 v[160:161], v[50:51], v[50:51]
	v_pk_mul_f32 v[162:163], v[48:49], v[48:49]
	v_mul_f32_e32 v152, v52, v52
	v_mul_f32_e32 v156, v53, v53
	v_mul_f32_e32 v30, v54, v54
	v_mul_f32_e32 v18, v55, v55
	v_pk_mov_b32 v[158:159], v[162:163], v[160:161] op_sel:[1,0]
	v_mov_b32_e32 v163, v161
	v_pk_add_f32 v[148:149], v[152:153], v[156:157]
	v_pk_add_f32 v[18:19], v[30:31], v[18:19]
	v_mul_f32_e32 v164, v44, v44
	v_mul_f32_e32 v166, v46, v46
	v_pk_add_f32 v[150:151], v[158:159], v[162:163]
	v_pk_add_f32 v[18:19], v[148:149], v[18:19]
	v_pk_fma_f32 v[160:161], v[44:45], v[44:45], v[164:165] op_sel_hi:[1,1,0]
	v_pk_fma_f32 v[164:165], v[46:47], v[46:47], v[166:167] op_sel_hi:[1,1,0]
	v_pk_add_f32 v[150:151], v[150:151], v[150:151] op_sel_hi:[0,1]
	v_pk_add_f32 v[18:19], v[18:19], v[18:19] op_sel_hi:[0,1]
	v_pk_mul_f32 v[168:169], v[38:39], v[38:39]
	v_pk_mul_f32 v[170:171], v[36:37], v[36:37]
	v_mul_f32_e32 v160, v40, v40
	v_mul_f32_e32 v164, v41, v41
	v_mul_f32_e32 v150, v42, v42
	v_mul_f32_e32 v18, v43, v43
	v_pk_mov_b32 v[166:167], v[170:171], v[168:169] op_sel:[1,0]
; #define GAS __attribute__((address_space(1)))
; __device__ __forceinline__ void ln_stats(const v4f (&v)[16], float& mean, float& rstd) {
;     ...
;     for (int j = 0; j < 16; ++j) { const v4f d = v[j] - mean; s2 += (d.x * d.x + d.y * d.y) + (d.z * d.z + d.w * d.w); }
;     rstd = 1.0f / sqrtf(wave_sum(s2) * (1.f / D_MODEL) + LN_EPS);
; __device__ __forceinline__ void phase_ln_final(const Ctx& X, float* io, const float* g, const float* bt) {
;     ...
;         const GAS v4f* gp = (const GAS v4f*)g + X.lane; const GAS v4f* bp = (const GAS v4f*)bt + X.lane;
; #pragma unroll
;         for (int j = 0; j < 16; ++j) rr[64 * j] = (v[j] - mean) * rstd * gp[64 * j] + bp[64 * j];
	v_mov_b32_e32 v171, v169
	v_pk_add_f32 v[152:153], v[160:161], v[164:165]
	v_pk_add_f32 v[18:19], v[150:151], v[18:19]
	v_mul_f32_e32 v172, v32, v32
	v_mul_f32_e32 v174, v34, v34
	v_pk_add_f32 v[154:155], v[166:167], v[170:171]
	v_pk_add_f32 v[18:19], v[152:153], v[18:19]
	v_pk_fma_f32 v[168:169], v[32:33], v[32:33], v[172:173] op_sel_hi:[1,1,0]
	v_pk_fma_f32 v[172:173], v[34:35], v[34:35], v[174:175] op_sel_hi:[1,1,0]
	v_pk_add_f32 v[154:155], v[154:155], v[154:155] op_sel_hi:[0,1]
	v_pk_add_f32 v[18:19], v[18:19], v[18:19] op_sel_hi:[0,1]
	v_pk_mul_f32 v[176:177], v[26:27], v[26:27]
	v_pk_mul_f32 v[178:179], v[8:9], v[8:9]
	v_mul_f32_e32 v168, v28, v28
	v_mul_f32_e32 v172, v29, v29
	v_mul_f32_e32 v154, v12, v12
	v_mul_f32_e32 v18, v13, v13
	v_pk_mov_b32 v[174:175], v[178:179], v[176:177] op_sel:[1,0]
	v_mov_b32_e32 v179, v177
	v_pk_add_f32 v[156:157], v[168:169], v[172:173]
	v_pk_add_f32 v[18:19], v[154:155], v[18:19]
	v_mul_f32_e32 v180, v4, v4
	v_mul_f32_e32 v182, v22, v22
	v_pk_add_f32 v[158:159], v[174:175], v[178:179]
	v_pk_add_f32 v[18:19], v[156:157], v[18:19]
	v_pk_fma_f32 v[176:177], v[4:5], v[4:5], v[180:181] op_sel_hi:[1,1,0]
	v_pk_fma_f32 v[180:181], v[22:23], v[22:23], v[182:183] op_sel_hi:[1,1,0]
	v_pk_add_f32 v[158:159], v[158:159], v[158:159] op_sel_hi:[0,1]
	v_pk_add_f32 v[18:19], v[18:19], v[18:19] op_sel_hi:[0,1]
	v_mul_f32_e32 v176, v16, v16
	v_mul_f32_e32 v180, v17, v17
	v_mul_f32_e32 v158, v2, v2
	v_mul_f32_e32 v18, v3, v3
	v_pk_add_f32 v[160:161], v[176:177], v[180:181]
	v_pk_add_f32 v[18:19], v[158:159], v[18:19]
	s_nop 0
	v_pk_add_f32 v[18:19], v[160:161], v[18:19]
	s_nop 0
	v_add_f32_e32 v18, v18, v19
	ds_bpermute_b32 v19, v132, v18
	s_waitcnt lgkmcnt(0)
	v_add_f32_e32 v18, v18, v19
	ds_bpermute_b32 v19, v133, v18
	s_waitcnt lgkmcnt(0)
	v_add_f32_e32 v18, v18, v19
	ds_bpermute_b32 v19, v134, v18
	s_waitcnt lgkmcnt(0)
	v_add_f32_e32 v18, v18, v19
	ds_bpermute_b32 v19, v135, v18
	s_waitcnt lgkmcnt(0)
	v_add_f32_e32 v18, v18, v19
	ds_bpermute_b32 v19, v136, v18
	s_waitcnt lgkmcnt(0)
	v_add_f32_e32 v18, v18, v19
	ds_bpermute_b32 v19, v137, v18
	s_waitcnt lgkmcnt(0)
	v_add_f32_e32 v18, v18, v19
	v_fmamk_f32 v18, v18, 0x39800000, v138
	v_mul_f32_e32 v19, 0x4f800000, v18
	v_cmp_gt_f32_e32 vcc, s3, v18
	s_nop 1
	v_cndmask_b32_e32 v18, v18, v19, vcc
	v_sqrt_f32_e32 v19, v18
	s_nop 0
	v_add_u32_e32 v20, -1, v19
	v_add_u32_e32 v21, 1, v19
	v_fma_f32 v24, -v20, v19, v18
	v_fma_f32 v25, -v21, v19, v18
	v_cmp_ge_f32_e64 s[0:1], 0, v24
	s_nop 1
	v_cndmask_b32_e64 v19, v19, v20, s[0:1]
	v_cmp_lt_f32_e64 s[0:1], 0, v25
	s_nop 1
	v_cndmask_b32_e64 v19, v19, v21, s[0:1]
	v_mul_f32_e32 v20, 0x37800000, v19
	v_cndmask_b32_e32 v19, v19, v20, vcc
	v_cmp_class_f32_e32 vcc, v18, v139
	s_nop 1
	v_cndmask_b32_e32 v18, v19, v18, vcc
	v_div_scale_f32 v19, s[0:1], v18, v18, 1.0
	v_rcp_f32_e32 v21, v19
	v_div_scale_f32 v20, vcc, 1.0, v18, 1.0
	v_fma_f32 v24, -v19, v21, 1.0
	v_fmac_f32_e32 v21, v24, v21
	v_mul_f32_e32 v24, v20, v21
	v_fma_f32 v25, -v19, v24, v20
	v_fmac_f32_e32 v24, v25, v21
	v_fma_f32 v19, -v19, v24, v20
	v_div_fmas_f32 v19, v19, v21, v24
	v_div_fixup_f32 v18, v19, v18, 1.0
	v_pk_mul_f32 v[20:21], v[140:141], v[18:19] op_sel_hi:[1,0]
	v_pk_mul_f32 v[14:15], v[14:15], v[18:19] op_sel_hi:[1,0]
	v_pk_fma_f32 v[64:65], v[64:65], v[20:21], v[68:69]
	v_pk_fma_f32 v[66:67], v[66:67], v[14:15], v[70:71]
	global_store_dwordx4 v[124:125], v[64:67], off
	s_waitcnt vmcnt(1)
; #define GAS __attribute__((address_space(1)))
; __device__ __forceinline__ void phase_ln_final(const Ctx& X, float* io, const float* g, const float* bt) {
;     ...
;         const GAS v4f* gp = (const GAS v4f*)g + X.lane; const GAS v4f* bp = (const GAS v4f*)bt + X.lane;
; #pragma unroll
;         for (int j = 0; j < 16; ++j) rr[64 * j] = (v[j] - mean) * rstd * gp[64 * j] + bp[64 * j];
	s_nop 0
	v_pk_mul_f32 v[10:11], v[10:11], v[18:19] op_sel_hi:[1,0]
	v_pk_mul_f32 v[14:15], v[142:143], v[18:19] op_sel_hi:[1,0]
	v_pk_mul_f32 v[6:7], v[6:7], v[18:19] op_sel_hi:[1,0]
	v_pk_mul_f32 v[0:1], v[0:1], v[18:19] op_sel_hi:[1,0]
	v_pk_mul_f32 v[4:5], v[4:5], v[18:19] op_sel_hi:[1,0]
	v_pk_mul_f32 v[2:3], v[2:3], v[18:19] op_sel_hi:[1,0]
	v_pk_fma_f32 v[64:65], v[186:187], v[14:15], v[190:191]
	v_pk_fma_f32 v[66:67], v[188:189], v[10:11], v[192:193]
	global_store_dwordx4 v[124:125], v[64:67], off offset:1024
	s_nop 0
	v_pk_mul_f32 v[10:11], v[144:145], v[18:19] op_sel_hi:[1,0]
	v_pk_fma_f32 v[66:67], v[196:197], v[6:7], v[200:201]
	v_pk_fma_f32 v[64:65], v[194:195], v[10:11], v[198:199]
	global_store_dwordx4 v[124:125], v[64:67], off offset:2048
	s_nop 0
	v_pk_mul_f32 v[6:7], v[146:147], v[18:19] op_sel_hi:[1,0]
	v_pk_fma_f32 v[64:65], v[202:203], v[0:1], v[206:207]
	v_pk_fma_f32 v[66:67], v[204:205], v[6:7], v[208:209]
	global_store_dwordx4 v[124:125], v[64:67], off offset:3072
	s_nop 0
	v_pk_mul_f32 v[0:1], v[62:63], v[18:19] op_sel_hi:[1,0]
	v_pk_mul_f32 v[6:7], v[60:61], v[18:19] op_sel_hi:[1,0]
	v_lshl_add_u64 v[124:125], v[124:125], 0, s[6:7]
	v_pk_fma_f32 v[60:61], v[210:211], v[6:7], v[214:215]
	v_pk_fma_f32 v[62:63], v[212:213], v[0:1], v[216:217]
	global_store_dwordx4 v[126:127], v[60:63], off
	s_nop 0
	v_pk_mul_f32 v[0:1], v[58:59], v[18:19] op_sel_hi:[1,0]
	v_pk_mul_f32 v[6:7], v[56:57], v[18:19] op_sel_hi:[1,0]
	v_pk_fma_f32 v[58:59], v[220:221], v[0:1], v[224:225]
	v_pk_fma_f32 v[56:57], v[218:219], v[6:7], v[222:223]
	global_store_dwordx4 v[126:127], v[56:59], off offset:1024
	s_nop 0
	v_pk_mul_f32 v[0:1], v[54:55], v[18:19] op_sel_hi:[1,0]
	v_pk_mul_f32 v[6:7], v[52:53], v[18:19] op_sel_hi:[1,0]
	v_pk_fma_f32 v[54:55], v[228:229], v[0:1], v[232:233]
	v_pk_fma_f32 v[52:53], v[226:227], v[6:7], v[230:231]
	global_store_dwordx4 v[126:127], v[52:55], off offset:2048
	s_nop 0
	v_pk_mul_f32 v[0:1], v[50:51], v[18:19] op_sel_hi:[1,0]
	v_pk_mul_f32 v[6:7], v[48:49], v[18:19] op_sel_hi:[1,0]
	v_pk_fma_f32 v[50:51], v[236:237], v[0:1], v[240:241]
	v_pk_fma_f32 v[48:49], v[234:235], v[6:7], v[238:239]
	global_store_dwordx4 v[126:127], v[48:51], off offset:3072
	s_nop 0
	v_pk_mul_f32 v[0:1], v[46:47], v[18:19] op_sel_hi:[1,0]
	v_pk_mul_f32 v[6:7], v[44:45], v[18:19] op_sel_hi:[1,0]
	v_pk_fma_f32 v[46:47], v[244:245], v[0:1], v[248:249]
	v_pk_fma_f32 v[44:45], v[242:243], v[6:7], v[246:247]
	global_store_dwordx4 v[130:131], v[44:47], off
	global_load_dwordx4 v[44:47], v[96:97], off
	s_nop 0
	global_load_dwordx4 v[48:51], v[98:99], off
	v_pk_mul_f32 v[0:1], v[42:43], v[18:19] op_sel_hi:[1,0]
	v_pk_mul_f32 v[6:7], v[40:41], v[18:19] op_sel_hi:[1,0]
	s_waitcnt vmcnt(0)
	v_pk_fma_f32 v[42:43], v[46:47], v[0:1], v[50:51]
	v_pk_fma_f32 v[40:41], v[44:45], v[6:7], v[48:49]
	global_store_dwordx4 v[130:131], v[40:43], off offset:1024
	global_load_dwordx4 v[40:43], v[100:101], off
	s_nop 0
	global_load_dwordx4 v[44:47], v[102:103], off
	v_pk_mul_f32 v[0:1], v[38:39], v[18:19] op_sel_hi:[1,0]
	v_pk_mul_f32 v[6:7], v[36:37], v[18:19] op_sel_hi:[1,0]
	s_waitcnt vmcnt(0)
	v_pk_fma_f32 v[38:39], v[42:43], v[0:1], v[46:47]
	v_pk_fma_f32 v[36:37], v[40:41], v[6:7], v[44:45]
	global_store_dwordx4 v[130:131], v[36:39], off offset:2048
	global_load_dwordx4 v[36:39], v[104:105], off
	s_nop 0
	global_load_dwordx4 v[40:43], v[106:107], off
	v_pk_mul_f32 v[0:1], v[34:35], v[18:19] op_sel_hi:[1,0]
	v_pk_mul_f32 v[6:7], v[32:33], v[18:19] op_sel_hi:[1,0]
	s_waitcnt vmcnt(0)
	v_pk_fma_f32 v[32:33], v[38:39], v[0:1], v[42:43]
	v_pk_fma_f32 v[30:31], v[36:37], v[6:7], v[40:41]
	global_store_dwordx4 v[130:131], v[30:33], off offset:3072
	global_load_dwordx4 v[30:33], v[108:109], off
	s_nop 0
	global_load_dwordx4 v[34:37], v[110:111], off
	v_pk_mul_f32 v[0:1], v[12:13], v[18:19] op_sel_hi:[1,0]
	v_pk_mul_f32 v[6:7], v[28:29], v[18:19] op_sel_hi:[1,0]
	s_waitcnt vmcnt(0)
	v_pk_fma_f32 v[12:13], v[0:1], v[32:33], v[36:37]
	v_pk_fma_f32 v[10:11], v[6:7], v[30:31], v[34:35]
	global_store_dwordx4 v[128:129], v[10:13], off
	global_load_dwordx4 v[10:13], v[112:113], off
	s_nop 0
	global_load_dwordx4 v[28:31], v[114:115], off
	v_pk_mul_f32 v[0:1], v[26:27], v[18:19] op_sel_hi:[1,0]
	v_pk_mul_f32 v[6:7], v[8:9], v[18:19] op_sel_hi:[1,0]
	s_waitcnt vmcnt(0)
	v_pk_fma_f32 v[8:9], v[0:1], v[12:13], v[30:31]
	v_pk_fma_f32 v[6:7], v[6:7], v[10:11], v[28:29]
	global_store_dwordx4 v[128:129], v[6:9], off offset:1024
	global_load_dwordx4 v[6:9], v[116:117], off
	s_nop 0
	global_load_dwordx4 v[10:13], v[118:119], off
	v_pk_mul_f32 v[0:1], v[22:23], v[18:19] op_sel_hi:[1,0]
	s_waitcnt vmcnt(0)
	v_pk_fma_f32 v[4:5], v[4:5], v[6:7], v[10:11]
	v_pk_fma_f32 v[6:7], v[0:1], v[8:9], v[12:13]
	global_store_dwordx4 v[128:129], v[4:7], off offset:2048
	global_load_dwordx4 v[4:7], v[120:121], off
	s_nop 0
	global_load_dwordx4 v[8:11], v[122:123], off
	v_pk_mul_f32 v[0:1], v[16:17], v[18:19] op_sel_hi:[1,0]
	s_waitcnt vmcnt(0)
	v_pk_fma_f32 v[2:3], v[2:3], v[6:7], v[10:11]
	v_pk_fma_f32 v[0:1], v[0:1], v[4:5], v[8:9]
	global_store_dwordx4 v[128:129], v[0:3], off offset:3072
	s_cbranch_scc1 .LBB0_1392
